# b0L4
# speedup vs baseline: 1.0099x; 1.0099x over previous
; #define PG8_STAGE(bufoff, gbase, voff) do { _Pragma("unroll") for (int _i = 0; _i < 2; ++_i) \
;         __builtin_amdgcn_global_load_lds((const unsigned*)((const char*)(gbase) + (voff)[_i]), (LAS unsigned*)(lds + (bufoff) + ldsw + _i * 8192), 16, 0, 0); } while (0)
; #define PG8_LDA(dst, b, h) do { _Pragma("unroll") for (int m = 0; m < 4; ++m) _Pragma("unroll") for (int k = 0; k < 2; ++k) dst[m][k] = *(const LAS bf16x8*)(lds + PG8_SA(b, h) + aoff + m * 2048 + k * 1024); } while (0)
; #define PG8_LDB(dst, b, h) do { _Pragma("unroll") for (int n = 0; n < 2; ++n) _Pragma("unroll") for (int k = 0; k < 2; ++k) dst[n][k] = *(const LAS bf16x8*)(lds + PG8_SB(b, h) + boff + n * 2048 + k * 1024); } while (0)
; #define PG8_MMA(ai, bj, At, Bt) do { __builtin_amdgcn_s_setprio(1); _Pragma("unroll") for (int m = 0; m < 4; ++m) _Pragma("unroll") for (int n = 0; n < 2; ++n) _Pragma("unroll") for (int k = 0; k < 2; ++k) \
;         acc[ai][bj][m][n] = __builtin_amdgcn_mfma_f32_16x16x32_bf16(Bt[n][k], At[m][k], acc[ai][bj][m][n], 0, 0, 0); __builtin_amdgcn_s_setprio(0); } while (0)
; #define PG8_BAR __builtin_amdgcn_s_barrier()
; template <class Epi, class Job>
; __device__ __forceinline__ void gemm_phase(LAS unsigned char* lds, const Job& S, const Epi& E) {
;     ...
;         const bool has_next = S.next(ui + 1, nxt);
;         const char* nA = has_next ? nxt.a : cA; const char* nB = has_next ? nxt.b : cB;
;         for (int t = 0; t < nt; t += 2) {
;             const bool last = (t == nt - 2);
;             const char* a1 = cA + (size_t)(t + 1) * kstep;
;             const char* a2 = last ? nA : cA + (size_t)(t + 2) * kstep; const char* b2 = last ? nB : cB + (size_t)(t + 2) * kstep;
;             const char* a3 = a2 + kstep; const char* b3 = b2 + kstep;
;             PG8_LDB(B0, 0, 0); PG8_SCHED; PG8_LDA(At, 0, 0); PG8_STAGE(PG8_SA(1, 1), a1 + hstepA, voffA);
;             PG8_WAIT_L(8); PG8_BAR; PG8_WAIT_L(0); PG8_MMA(0, 0, At, B0); PG8_BAR; PG8_SCHED;
;             PG8_LDB(B1, 0, 1); PG8_STAGE(PG8_SB(0, 0), b2, voffB);
;             PG8_BAR; PG8_WAIT_L(0); PG8_MMA(0, 1, At, B1); PG8_BAR;
;             PG8_LDA(At, 0, 1); PG8_STAGE(PG8_SA(0, 0), a2, voffA);
;             PG8_BAR; PG8_WAIT_L(0); PG8_MMA(1, 0, At, B0); PG8_BAR; PG8_SCHED;
;             PG8_STAGE(PG8_SB(0, 1), b2 + hstepB, voffB);
;             PG8_WAIT_V(6); PG8_BAR; PG8_MMA(1, 1, At, B1); PG8_BAR;
.LBB0_186:
	s_add_i32 m0, s52, 0xc000
	s_nop 0
	global_load_lds_dwordx4 v144, s[28:29]
	s_add_i32 m0, s52, 0xe000
	s_nop 0
	global_load_lds_dwordx4 v146, s[28:29]
	s_add_u32 s36, s28, 0xfff00080
	s_addc_u32 s37, s29, -1
	s_cmp_eq_u32 s68, 60
	s_cselect_b32 s47, s23, s37
	s_cselect_b32 s46, s22, s36
	s_cselect_b32 s37, s25, s67
	s_cselect_b32 s36, s24, s27
	ds_read_b128 v[190:193], v155 offset:1024
	ds_read_b128 v[198:201], v155 offset:3072
	ds_read_b128 v[206:209], v155 offset:5120
	ds_read_b128 v[214:217], v155 offset:7168
	s_waitcnt lgkmcnt(8)
	s_waitcnt lgkmcnt(0)
	s_setprio 1
	s_barrier
	v_mfma_f32_16x16x32_bf16 v[124:127], v[158:161], v[186:189], v[124:127]
	ds_read_b128 v[218:221], v156
	v_mfma_f32_16x16x32_bf16 v[120:123], v[178:181], v[186:189], v[120:123]
	v_mfma_f32_16x16x32_bf16 v[112:115], v[158:161], v[194:197], v[112:115]
	ds_read_b128 v[222:225], v156 offset:1024
	v_mfma_f32_16x16x32_bf16 v[104:107], v[178:181], v[194:197], v[104:107]
	v_mfma_f32_16x16x32_bf16 v[100:103], v[158:161], v[202:205], v[100:103]
	ds_read_b128 v[226:229], v156 offset:2048
	v_mfma_f32_16x16x32_bf16 v[92:95], v[178:181], v[202:205], v[92:95]
	v_mfma_f32_16x16x32_bf16 v[84:87], v[158:161], v[210:213], v[84:87]
	ds_read_b128 v[230:233], v156 offset:3072
	v_mfma_f32_16x16x32_bf16 v[76:79], v[178:181], v[210:213], v[76:79]
	v_mfma_f32_16x16x32_bf16 v[124:127], v[174:177], v[190:193], v[124:127]
	v_mfma_f32_16x16x32_bf16 v[120:123], v[182:185], v[190:193], v[120:123]
	v_mfma_f32_16x16x32_bf16 v[112:115], v[174:177], v[198:201], v[112:115]
	v_mfma_f32_16x16x32_bf16 v[104:107], v[182:185], v[198:201], v[104:107]
	v_mfma_f32_16x16x32_bf16 v[100:103], v[174:177], v[206:209], v[100:103]
	v_mfma_f32_16x16x32_bf16 v[92:95], v[182:185], v[206:209], v[92:95]
	v_mfma_f32_16x16x32_bf16 v[84:87], v[174:177], v[214:217], v[84:87]
	v_mfma_f32_16x16x32_bf16 v[76:79], v[182:185], v[214:217], v[76:79]
	s_barrier
	s_setprio 0
	s_add_i32 s69, s60, s49
	s_mov_b32 m0, s69
	s_nop 0
	global_load_lds_dwordx4 v136, s[36:37]
	s_add_i32 m0, s69, 0x2000
	s_nop 0
	global_load_lds_dwordx4 v140, s[36:37]
	s_waitcnt lgkmcnt(0)
	s_setprio 1
	s_barrier
	v_mfma_f32_16x16x32_bf16 v[116:119], v[218:221], v[186:189], v[116:119]
	v_mfma_f32_16x16x32_bf16 v[108:111], v[226:229], v[186:189], v[108:111]
	v_mfma_f32_16x16x32_bf16 v[96:99], v[218:221], v[194:197], v[96:99]
	v_mfma_f32_16x16x32_bf16 v[88:91], v[226:229], v[194:197], v[88:91]
	v_mfma_f32_16x16x32_bf16 v[80:83], v[218:221], v[202:205], v[80:83]
	v_mfma_f32_16x16x32_bf16 v[72:75], v[226:229], v[202:205], v[72:75]
	v_mfma_f32_16x16x32_bf16 v[68:71], v[218:221], v[210:213], v[68:71]
	v_mfma_f32_16x16x32_bf16 v[64:67], v[226:229], v[210:213], v[64:67]
	v_mfma_f32_16x16x32_bf16 v[116:119], v[222:225], v[190:193], v[116:119]
	ds_read_b128 v[186:189], v155 offset:16384
	v_mfma_f32_16x16x32_bf16 v[108:111], v[230:233], v[190:193], v[108:111]
	v_mfma_f32_16x16x32_bf16 v[96:99], v[222:225], v[198:201], v[96:99]
	ds_read_b128 v[194:197], v155 offset:18432
	v_mfma_f32_16x16x32_bf16 v[88:91], v[230:233], v[198:201], v[88:91]
	v_mfma_f32_16x16x32_bf16 v[80:83], v[222:225], v[206:209], v[80:83]
	ds_read_b128 v[202:205], v155 offset:20480
	v_mfma_f32_16x16x32_bf16 v[72:75], v[230:233], v[206:209], v[72:75]
	v_mfma_f32_16x16x32_bf16 v[68:71], v[222:225], v[214:217], v[68:71]
	ds_read_b128 v[210:213], v155 offset:22528
	v_mfma_f32_16x16x32_bf16 v[64:67], v[230:233], v[214:217], v[64:67]
	s_barrier
	s_setprio 0
	s_mov_b32 m0, s52
	s_mov_b64 s[100:101], s[46:47]
	global_load_lds_dwordx4 v134, s[46:47]
	s_mov_b32 m0, s53
	s_nop 0
	global_load_lds_dwordx4 v138, s[46:47]
	ds_read_b128 v[190:193], v155 offset:17408
	ds_read_b128 v[198:201], v155 offset:19456
	ds_read_b128 v[206:209], v155 offset:21504
	ds_read_b128 v[214:217], v155 offset:23552
	s_waitcnt vmcnt(8)
	s_waitcnt lgkmcnt(0)
	s_setprio 1
	s_barrier
	v_mfma_f32_16x16x32_bf16 v[60:63], v[158:161], v[186:189], v[60:63]
	v_mfma_f32_16x16x32_bf16 v[56:59], v[178:181], v[186:189], v[56:59]
	v_mfma_f32_16x16x32_bf16 v[52:55], v[158:161], v[194:197], v[52:55]
	v_mfma_f32_16x16x32_bf16 v[44:47], v[178:181], v[194:197], v[44:47]
	v_mfma_f32_16x16x32_bf16 v[36:39], v[158:161], v[202:205], v[36:39]
	v_mfma_f32_16x16x32_bf16 v[28:31], v[178:181], v[202:205], v[28:31]
	v_mfma_f32_16x16x32_bf16 v[20:23], v[158:161], v[210:213], v[20:23]
	v_mfma_f32_16x16x32_bf16 v[12:15], v[178:181], v[210:213], v[12:15]
	v_mfma_f32_16x16x32_bf16 v[60:63], v[174:177], v[190:193], v[60:63]
	v_mfma_f32_16x16x32_bf16 v[56:59], v[182:185], v[190:193], v[56:59]
	v_mfma_f32_16x16x32_bf16 v[52:55], v[174:177], v[198:201], v[52:55]
	v_mfma_f32_16x16x32_bf16 v[44:47], v[182:185], v[198:201], v[44:47]
	v_mfma_f32_16x16x32_bf16 v[36:39], v[174:177], v[206:209], v[36:39]
	v_mfma_f32_16x16x32_bf16 v[28:31], v[182:185], v[206:209], v[28:31]
	v_mfma_f32_16x16x32_bf16 v[20:23], v[174:177], v[214:217], v[20:23]
	v_mfma_f32_16x16x32_bf16 v[12:15], v[182:185], v[214:217], v[12:15]
	s_barrier
	s_setprio 0
	s_add_u32 s70, s36, 0x100000
	s_addc_u32 s71, s37, 0
	s_add_i32 s69, s61, s49
	s_mov_b32 m0, s69
	s_nop 0
	global_load_lds_dwordx4 v136, s[70:71]
	s_add_i32 m0, s69, 0x2000
	s_nop 0
	global_load_lds_dwordx4 v140, s[70:71]
	v_add_u32_e32 v157, 0x18000, v153
	ds_read_b128 v[158:161], v157
	ds_read_b128 v[174:177], v157 offset:1024
	ds_read_b128 v[178:181], v157 offset:2048
	ds_read_b128 v[182:185], v157 offset:3072
	s_waitcnt vmcnt(6)
	s_setprio 1
	s_barrier
; #define PG8_STAGE(bufoff, gbase, voff) do { _Pragma("unroll") for (int _i = 0; _i < 2; ++_i) \
;         __builtin_amdgcn_global_load_lds((const unsigned*)((const char*)(gbase) + (voff)[_i]), (LAS unsigned*)(lds + (bufoff) + ldsw + _i * 8192), 16, 0, 0); } while (0)
; #define PG8_LDA(dst, b, h) do { _Pragma("unroll") for (int m = 0; m < 4; ++m) _Pragma("unroll") for (int k = 0; k < 2; ++k) dst[m][k] = *(const LAS bf16x8*)(lds + PG8_SA(b, h) + aoff + m * 2048 + k * 1024); } while (0)
; #define PG8_LDB(dst, b, h) do { _Pragma("unroll") for (int n = 0; n < 2; ++n) _Pragma("unroll") for (int k = 0; k < 2; ++k) dst[n][k] = *(const LAS bf16x8*)(lds + PG8_SB(b, h) + boff + n * 2048 + k * 1024); } while (0)
; #define PG8_MMA(ai, bj, At, Bt) do { __builtin_amdgcn_s_setprio(1); _Pragma("unroll") for (int m = 0; m < 4; ++m) _Pragma("unroll") for (int n = 0; n < 2; ++n) _Pragma("unroll") for (int k = 0; k < 2; ++k) \
;         acc[ai][bj][m][n] = __builtin_amdgcn_mfma_f32_16x16x32_bf16(Bt[n][k], At[m][k], acc[ai][bj][m][n], 0, 0, 0); __builtin_amdgcn_s_setprio(0); } while (0)
; #define PG8_WAIT_V(n) asm volatile("s_waitcnt vmcnt(" #n ")" ::: "memory")
; #define PG8_WAIT_L(n) asm volatile("s_waitcnt lgkmcnt(" #n ")" ::: "memory")
; #define PG8_BAR __builtin_amdgcn_s_barrier()
; #define PG8_SCHED __builtin_amdgcn_sched_barrier(0)
; template <class Epi, class Job>
; __device__ __forceinline__ void gemm_phase(LAS unsigned char* lds, const Job& S, const Epi& E) {
;     ...
;             PG8_WAIT_V(6); PG8_BAR; PG8_MMA(1, 1, At, B1); PG8_BAR;
;             PG8_LDB(B0, 1, 0); PG8_SCHED; PG8_LDA(At, 1, 0); PG8_STAGE(PG8_SA(0, 1), a2 + hstepA, voffA);
;             PG8_WAIT_L(8); PG8_BAR; PG8_WAIT_L(0); PG8_MMA(0, 0, At, B0); PG8_BAR; PG8_SCHED;
;             PG8_LDB(B1, 1, 1); PG8_STAGE(PG8_SB(1, 0), b3, voffB);
;             PG8_BAR; PG8_WAIT_L(0); PG8_MMA(0, 1, At, B1); PG8_BAR;
;             PG8_LDA(At, 1, 1); PG8_STAGE(PG8_SA(1, 0), a3, voffA);
;             PG8_BAR; PG8_WAIT_L(0); PG8_MMA(1, 0, At, B0); PG8_BAR; PG8_SCHED;
	v_mfma_f32_16x16x32_bf16 v[48:51], v[218:221], v[186:189], v[48:51]
	v_mfma_f32_16x16x32_bf16 v[40:43], v[226:229], v[186:189], v[40:43]
	v_mfma_f32_16x16x32_bf16 v[32:35], v[218:221], v[194:197], v[32:35]
	v_mfma_f32_16x16x32_bf16 v[24:27], v[226:229], v[194:197], v[24:27]
	v_mfma_f32_16x16x32_bf16 v[16:19], v[218:221], v[202:205], v[16:19]
	v_mfma_f32_16x16x32_bf16 v[8:11], v[226:229], v[202:205], v[8:11]
	v_mfma_f32_16x16x32_bf16 v[4:7], v[218:221], v[210:213], v[4:7]
	v_mfma_f32_16x16x32_bf16 v[0:3], v[226:229], v[210:213], v[0:3]
	v_mfma_f32_16x16x32_bf16 v[48:51], v[222:225], v[190:193], v[48:51]
	ds_read_b128 v[186:189], v155 offset:32768
	v_mfma_f32_16x16x32_bf16 v[40:43], v[230:233], v[190:193], v[40:43]
	v_mfma_f32_16x16x32_bf16 v[32:35], v[222:225], v[198:201], v[32:35]
	ds_read_b128 v[194:197], v155 offset:34816
	v_mfma_f32_16x16x32_bf16 v[24:27], v[230:233], v[198:201], v[24:27]
	v_mfma_f32_16x16x32_bf16 v[16:19], v[222:225], v[206:209], v[16:19]
	ds_read_b128 v[202:205], v155 offset:36864
	v_mfma_f32_16x16x32_bf16 v[8:11], v[230:233], v[206:209], v[8:11]
	v_mfma_f32_16x16x32_bf16 v[4:7], v[222:225], v[214:217], v[4:7]
	ds_read_b128 v[210:213], v155 offset:38912
	v_mfma_f32_16x16x32_bf16 v[0:3], v[230:233], v[214:217], v[0:3]
	s_barrier
	s_setprio 0
	s_add_i32 s69, 0, 0x18000
	v_add_u32_e32 v157, s69, v153
	s_add_u32 s46, s46, 0x100000
	s_addc_u32 s47, s47, 0
	s_mov_b32 m0, s54
	s_nop 0
	global_load_lds_dwordx4 v134, s[46:47]
	s_mov_b32 m0, s55
	s_nop 0
	global_load_lds_dwordx4 v138, s[46:47]
	ds_read_b128 v[190:193], v155 offset:33792
	ds_read_b128 v[198:201], v155 offset:35840
	ds_read_b128 v[206:209], v155 offset:37888
	ds_read_b128 v[214:217], v155 offset:39936
	s_waitcnt lgkmcnt(8)
	s_waitcnt lgkmcnt(0)
	s_setprio 1
	v_add_u32_e32 v157, 0x1c000, v153
	s_barrier
	v_mfma_f32_16x16x32_bf16 v[124:127], v[158:161], v[186:189], v[124:127]
	ds_read_b128 v[218:221], v157
	v_mfma_f32_16x16x32_bf16 v[120:123], v[178:181], v[186:189], v[120:123]
	v_mfma_f32_16x16x32_bf16 v[112:115], v[158:161], v[194:197], v[112:115]
	ds_read_b128 v[222:225], v157 offset:1024
	v_mfma_f32_16x16x32_bf16 v[104:107], v[178:181], v[194:197], v[104:107]
	v_mfma_f32_16x16x32_bf16 v[100:103], v[158:161], v[202:205], v[100:103]
	ds_read_b128 v[226:229], v157 offset:2048
	v_mfma_f32_16x16x32_bf16 v[92:95], v[178:181], v[202:205], v[92:95]
	v_mfma_f32_16x16x32_bf16 v[84:87], v[158:161], v[210:213], v[84:87]
	ds_read_b128 v[230:233], v157 offset:3072
	v_mfma_f32_16x16x32_bf16 v[76:79], v[178:181], v[210:213], v[76:79]
	v_mfma_f32_16x16x32_bf16 v[124:127], v[174:177], v[190:193], v[124:127]
	v_mfma_f32_16x16x32_bf16 v[120:123], v[182:185], v[190:193], v[120:123]
	v_mfma_f32_16x16x32_bf16 v[112:115], v[174:177], v[198:201], v[112:115]
	v_mfma_f32_16x16x32_bf16 v[104:107], v[182:185], v[198:201], v[104:107]
	v_mfma_f32_16x16x32_bf16 v[100:103], v[174:177], v[206:209], v[100:103]
	v_mfma_f32_16x16x32_bf16 v[92:95], v[182:185], v[206:209], v[92:95]
	v_mfma_f32_16x16x32_bf16 v[84:87], v[174:177], v[214:217], v[84:87]
	v_mfma_f32_16x16x32_bf16 v[76:79], v[182:185], v[214:217], v[76:79]
	s_barrier
	s_setprio 0
	s_add_i32 s46, 0, 0x1c000
	s_add_i32 s47, s69, s49
	v_add_u32_e32 v157, s46, v153
	s_add_u32 s98, s36, s10
	s_addc_u32 s99, s37, s11
	s_mov_b32 m0, s47
	s_nop 0
	global_load_lds_dwordx4 v136, s[98:99]
	s_add_i32 m0, s47, 0x2000
	s_nop 0
	global_load_lds_dwordx4 v140, s[98:99]
	s_waitcnt lgkmcnt(0)
	s_setprio 1
	s_barrier
	v_mfma_f32_16x16x32_bf16 v[116:119], v[218:221], v[186:189], v[116:119]
	v_mfma_f32_16x16x32_bf16 v[108:111], v[226:229], v[186:189], v[108:111]
	v_mfma_f32_16x16x32_bf16 v[96:99], v[218:221], v[194:197], v[96:99]
	v_mfma_f32_16x16x32_bf16 v[88:91], v[226:229], v[194:197], v[88:91]
	v_mfma_f32_16x16x32_bf16 v[80:83], v[218:221], v[202:205], v[80:83]
	v_mfma_f32_16x16x32_bf16 v[72:75], v[226:229], v[202:205], v[72:75]
	v_mfma_f32_16x16x32_bf16 v[68:71], v[218:221], v[210:213], v[68:71]
	v_mfma_f32_16x16x32_bf16 v[64:67], v[226:229], v[210:213], v[64:67]
	v_mfma_f32_16x16x32_bf16 v[116:119], v[222:225], v[190:193], v[116:119]
	ds_read_b128 v[186:189], v155 offset:49152
	v_mfma_f32_16x16x32_bf16 v[108:111], v[230:233], v[190:193], v[108:111]
	v_mfma_f32_16x16x32_bf16 v[96:99], v[222:225], v[198:201], v[96:99]
	ds_read_b128 v[194:197], v155 offset:51200
	v_mfma_f32_16x16x32_bf16 v[88:91], v[230:233], v[198:201], v[88:91]
	v_mfma_f32_16x16x32_bf16 v[80:83], v[222:225], v[206:209], v[80:83]
	ds_read_b128 v[202:205], v155 offset:53248
	v_mfma_f32_16x16x32_bf16 v[72:75], v[230:233], v[206:209], v[72:75]
	v_mfma_f32_16x16x32_bf16 v[68:71], v[222:225], v[214:217], v[68:71]
	ds_read_b128 v[210:213], v155 offset:55296
	v_mfma_f32_16x16x32_bf16 v[64:67], v[230:233], v[214:217], v[64:67]
	s_barrier
; #define PG8_STAGE(bufoff, gbase, voff) do { _Pragma("unroll") for (int _i = 0; _i < 2; ++_i) \
;         __builtin_amdgcn_global_load_lds((const unsigned*)((const char*)(gbase) + (voff)[_i]), (LAS unsigned*)(lds + (bufoff) + ldsw + _i * 8192), 16, 0, 0); } while (0)
; #define PG8_LDA(dst, b, h) do { _Pragma("unroll") for (int m = 0; m < 4; ++m) _Pragma("unroll") for (int k = 0; k < 2; ++k) dst[m][k] = *(const LAS bf16x8*)(lds + PG8_SA(b, h) + aoff + m * 2048 + k * 1024); } while (0)
; #define PG8_LDB(dst, b, h) do { _Pragma("unroll") for (int n = 0; n < 2; ++n) _Pragma("unroll") for (int k = 0; k < 2; ++k) dst[n][k] = *(const LAS bf16x8*)(lds + PG8_SB(b, h) + boff + n * 2048 + k * 1024); } while (0)
; #define PG8_WAIT_V(n) asm volatile("s_waitcnt vmcnt(" #n ")" ::: "memory")
; #define PG8_WAIT_L(n) asm volatile("s_waitcnt lgkmcnt(" #n ")" ::: "memory")
; #define PG8_BAR __builtin_amdgcn_s_barrier()
;     __device__ __forceinline__ void operator()(const f32x4 (&acc)[2][2][4][2], const Unit& u, int wr, int wc, int fr, int fq) const {
;         const int row0 = u.orow + wr * 64 + fr;
;         bf16_t* base; size_t rstride, bjstride;
;         if (u.ocol < 6144) { const int sect = u.ocol >> 11, hh0 = (u.ocol & 2047) >> 7, b = u.orow >= SEQ ? 1 : 0;
;             base = qkv + (size_t)sect * MTOK * 2048 + ((size_t)(b * 16 + hh0) * SEQ + (row0 & (SEQ - 1))) * 128 + wc * 32 + 8 * fq; rstride = 128; bjstride = (size_t)SEQ * 128; }
;         else { base = proj2 + (size_t)row0 * NP2 + (u.ocol - 6144) + wc * 32 + 8 * fq; rstride = NP2; bjstride = HALF; }
; template <class Epi, class Job>
; __device__ __forceinline__ void gemm_phase(LAS unsigned char* lds, const Job& S, const Epi& E) {
;     ...
;             PG8_LDB(B0, 1, 0); PG8_SCHED; PG8_LDA(At, 1, 0); PG8_STAGE(PG8_SA(0, 1), a2 + hstepA, voffA);
;             PG8_WAIT_L(8); PG8_BAR; PG8_WAIT_L(0); PG8_MMA(0, 0, At, B0); PG8_BAR; PG8_SCHED;
;             PG8_LDB(B1, 1, 1); PG8_STAGE(PG8_SB(1, 0), b3, voffB);
;             PG8_BAR; PG8_WAIT_L(0); PG8_MMA(0, 1, At, B1); PG8_BAR;
;             PG8_LDA(At, 1, 1); PG8_STAGE(PG8_SA(1, 0), a3, voffA);
;             PG8_BAR; PG8_WAIT_L(0); PG8_MMA(1, 0, At, B0); PG8_BAR; PG8_SCHED;
;             PG8_STAGE(PG8_SB(1, 1), b3 + hstepB, voffB);
;             PG8_WAIT_V(6); PG8_BAR; PG8_MMA(1, 1, At, B1); PG8_BAR;
;         }
;         E(acc, cur, wr, wc, fr, fq);
	s_setprio 0
	s_mov_b32 m0, s56
	s_add_u32 s100, s100, s10
	s_addc_u32 s101, s101, s11
	global_load_lds_dwordx4 v134, s[100:101]
	s_mov_b32 m0, s57
	s_nop 0
	global_load_lds_dwordx4 v138, s[100:101]
	ds_read_b128 v[190:193], v155 offset:50176
	ds_read_b128 v[198:201], v155 offset:52224
	ds_read_b128 v[206:209], v155 offset:54272
	ds_read_b128 v[214:217], v155 offset:56320
	s_waitcnt vmcnt(8)
	s_waitcnt lgkmcnt(0)
	s_setprio 1
	s_barrier
	v_mfma_f32_16x16x32_bf16 v[60:63], v[158:161], v[186:189], v[60:63]
	v_mfma_f32_16x16x32_bf16 v[56:59], v[178:181], v[186:189], v[56:59]
	v_mfma_f32_16x16x32_bf16 v[52:55], v[158:161], v[194:197], v[52:55]
	v_mfma_f32_16x16x32_bf16 v[44:47], v[178:181], v[194:197], v[44:47]
	v_mfma_f32_16x16x32_bf16 v[36:39], v[158:161], v[202:205], v[36:39]
	v_mfma_f32_16x16x32_bf16 v[28:31], v[178:181], v[202:205], v[28:31]
	v_mfma_f32_16x16x32_bf16 v[20:23], v[158:161], v[210:213], v[20:23]
	v_mfma_f32_16x16x32_bf16 v[12:15], v[178:181], v[210:213], v[12:15]
	v_mfma_f32_16x16x32_bf16 v[60:63], v[174:177], v[190:193], v[60:63]
	v_mfma_f32_16x16x32_bf16 v[56:59], v[182:185], v[190:193], v[56:59]
	v_mfma_f32_16x16x32_bf16 v[52:55], v[174:177], v[198:201], v[52:55]
	v_mfma_f32_16x16x32_bf16 v[44:47], v[182:185], v[198:201], v[44:47]
	v_mfma_f32_16x16x32_bf16 v[36:39], v[174:177], v[206:209], v[36:39]
	v_mfma_f32_16x16x32_bf16 v[28:31], v[182:185], v[206:209], v[28:31]
	v_mfma_f32_16x16x32_bf16 v[20:23], v[174:177], v[214:217], v[20:23]
	v_mfma_f32_16x16x32_bf16 v[12:15], v[182:185], v[214:217], v[12:15]
	s_barrier
	s_setprio 0
	s_add_u32 s36, s36, 0x100080
	s_addc_u32 s37, s37, 0
	s_add_i32 s46, s46, s49
	s_mov_b32 m0, s46
	s_nop 0
	global_load_lds_dwordx4 v136, s[36:37]
	s_add_i32 m0, s46, 0x2000
	s_nop 0
	global_load_lds_dwordx4 v140, s[36:37]
	ds_read_b128 v[158:161], v154
	ds_read_b128 v[174:177], v154 offset:1024
	ds_read_b128 v[178:181], v154 offset:2048
	ds_read_b128 v[182:185], v154 offset:3072
	s_waitcnt vmcnt(6)
	s_setprio 1
	s_barrier
	v_mfma_f32_16x16x32_bf16 v[48:51], v[218:221], v[186:189], v[48:51]
	v_mfma_f32_16x16x32_bf16 v[40:43], v[226:229], v[186:189], v[40:43]
	v_mfma_f32_16x16x32_bf16 v[32:35], v[218:221], v[194:197], v[32:35]
	v_mfma_f32_16x16x32_bf16 v[24:27], v[226:229], v[194:197], v[24:27]
	v_mfma_f32_16x16x32_bf16 v[16:19], v[218:221], v[202:205], v[16:19]
	v_mfma_f32_16x16x32_bf16 v[8:11], v[226:229], v[202:205], v[8:11]
	v_mfma_f32_16x16x32_bf16 v[4:7], v[218:221], v[210:213], v[4:7]
	v_mfma_f32_16x16x32_bf16 v[0:3], v[226:229], v[210:213], v[0:3]
	v_mfma_f32_16x16x32_bf16 v[48:51], v[222:225], v[190:193], v[48:51]
	ds_read_b128 v[186:189], v155
	v_mfma_f32_16x16x32_bf16 v[40:43], v[230:233], v[190:193], v[40:43]
	v_mfma_f32_16x16x32_bf16 v[32:35], v[222:225], v[198:201], v[32:35]
	ds_read_b128 v[194:197], v155 offset:2048
	v_mfma_f32_16x16x32_bf16 v[24:27], v[230:233], v[198:201], v[24:27]
	v_mfma_f32_16x16x32_bf16 v[16:19], v[222:225], v[206:209], v[16:19]
	ds_read_b128 v[202:205], v155 offset:4096
	v_mfma_f32_16x16x32_bf16 v[8:11], v[230:233], v[206:209], v[8:11]
	v_mfma_f32_16x16x32_bf16 v[4:7], v[222:225], v[214:217], v[4:7]
	ds_read_b128 v[210:213], v155 offset:6144
	v_mfma_f32_16x16x32_bf16 v[0:3], v[230:233], v[214:217], v[0:3]
	s_barrier
	s_setprio 0
	s_add_i32 s68, s68, 2
	s_add_u32 s28, s28, 0x100
	s_addc_u32 s29, s29, 0
	s_add_u32 s27, s27, 0x100
	s_addc_u32 s67, s67, 0
	s_cmp_gt_u32 s68, 61
	s_cbranch_scc0 .LBB0_186
	s_waitcnt lgkmcnt(0)
	v_add_u32_e32 v157, s66, v131
	s_cmpk_gt_i32 s26, 0x17ff
	s_mov_b64 s[28:29], -1
	s_cbranch_scc0 .LBB0_189
	v_mov_b64_e32 v[150:151], s[20:21]
	v_mad_i64_i32 v[150:151], s[28:29], v157, s62, v[150:151]
	s_mov_b32 s27, s9
	v_lshl_add_u64 v[150:151], s[26:27], 1, v[150:151]
	v_lshl_add_u64 v[150:151], v[150:151], 0, s[12:13]
	s_mov_b64 s[28:29], 0

; #define PG8_STAGE(bufoff, gbase, voff) do { _Pragma("unroll") for (int _i = 0; _i < 2; ++_i) \
;         __builtin_amdgcn_global_load_lds((const unsigned*)((const char*)(gbase) + (voff)[_i]), (LAS unsigned*)(lds + (bufoff) + ldsw + _i * 8192), 16, 0, 0); } while (0)
; #define PG8_LDA(dst, b, h) do { _Pragma("unroll") for (int m = 0; m < 4; ++m) _Pragma("unroll") for (int k = 0; k < 2; ++k) dst[m][k] = *(const LAS bf16x8*)(lds + PG8_SA(b, h) + aoff + m * 2048 + k * 1024); } while (0)
; #define PG8_LDB(dst, b, h) do { _Pragma("unroll") for (int n = 0; n < 2; ++n) _Pragma("unroll") for (int k = 0; k < 2; ++k) dst[n][k] = *(const LAS bf16x8*)(lds + PG8_SB(b, h) + boff + n * 2048 + k * 1024); } while (0)
; #define PG8_MMA(ai, bj, At, Bt) do { __builtin_amdgcn_s_setprio(1); _Pragma("unroll") for (int m = 0; m < 4; ++m) _Pragma("unroll") for (int n = 0; n < 2; ++n) _Pragma("unroll") for (int k = 0; k < 2; ++k) \
;         acc[ai][bj][m][n] = __builtin_amdgcn_mfma_f32_16x16x32_bf16(Bt[n][k], At[m][k], acc[ai][bj][m][n], 0, 0, 0); __builtin_amdgcn_s_setprio(0); } while (0)
; #define PG8_BAR __builtin_amdgcn_s_barrier()
; template <class Epi, class Job>
; __device__ __forceinline__ void gemm_phase(LAS unsigned char* lds, const Job& S, const Epi& E) {
;     ...
;         const bool has_next = S.next(ui + 1, nxt);
;         const char* nA = has_next ? nxt.a : cA; const char* nB = has_next ? nxt.b : cB;
;         for (int t = 0; t < nt; t += 2) {
;             const bool last = (t == nt - 2);
;             const char* a1 = cA + (size_t)(t + 1) * kstep;
;             const char* a2 = last ? nA : cA + (size_t)(t + 2) * kstep; const char* b2 = last ? nB : cB + (size_t)(t + 2) * kstep;
;             const char* a3 = a2 + kstep; const char* b3 = b2 + kstep;
;             PG8_LDB(B0, 0, 0); PG8_SCHED; PG8_LDA(At, 0, 0); PG8_STAGE(PG8_SA(1, 1), a1 + hstepA, voffA);
;             PG8_WAIT_L(8); PG8_BAR; PG8_WAIT_L(0); PG8_MMA(0, 0, At, B0); PG8_BAR; PG8_SCHED;
;             PG8_LDB(B1, 0, 1); PG8_STAGE(PG8_SB(0, 0), b2, voffB);
;             PG8_BAR; PG8_WAIT_L(0); PG8_MMA(0, 1, At, B1); PG8_BAR;
;             PG8_LDA(At, 0, 1); PG8_STAGE(PG8_SA(0, 0), a2, voffA);
;             PG8_BAR; PG8_WAIT_L(0); PG8_MMA(1, 0, At, B0); PG8_BAR; PG8_SCHED;
;             PG8_STAGE(PG8_SB(0, 1), b2 + hstepB, voffB);
;             PG8_WAIT_V(6); PG8_BAR; PG8_MMA(1, 1, At, B1); PG8_BAR;
.LBB0_457:
	s_add_i32 m0, s57, 0xc000
	s_nop 0
	global_load_lds_dwordx4 v132, s[36:37]
	s_add_i32 m0, s57, 0xe000
	s_nop 0
	global_load_lds_dwordx4 v142, s[36:37]
	s_add_u32 s46, s36, 0xfff00080
	s_addc_u32 s47, s37, -1
	s_cmp_eq_u32 s81, 60
	s_cselect_b32 s49, s29, s47
	s_cselect_b32 s48, s28, s46
	s_cselect_b32 s47, s31, s80
	s_cselect_b32 s46, s30, s79
	ds_read_b128 v[174:177], v151 offset:1024
	ds_read_b128 v[182:185], v151 offset:3072
	ds_read_b128 v[190:193], v151 offset:5120
	ds_read_b128 v[198:201], v151 offset:7168
	s_waitcnt lgkmcnt(8)
	s_waitcnt lgkmcnt(0)
	s_setprio 1
	s_barrier
	v_mfma_f32_16x16x32_bf16 v[124:127], v[154:157], v[170:173], v[124:127]
	ds_read_b128 v[202:205], v152
	v_mfma_f32_16x16x32_bf16 v[120:123], v[162:165], v[170:173], v[120:123]
	v_mfma_f32_16x16x32_bf16 v[116:119], v[154:157], v[178:181], v[116:119]
	ds_read_b128 v[206:209], v152 offset:1024
	v_mfma_f32_16x16x32_bf16 v[108:111], v[162:165], v[178:181], v[108:111]
	v_mfma_f32_16x16x32_bf16 v[100:103], v[154:157], v[186:189], v[100:103]
	ds_read_b128 v[210:213], v152 offset:2048
	v_mfma_f32_16x16x32_bf16 v[92:95], v[162:165], v[186:189], v[92:95]
	v_mfma_f32_16x16x32_bf16 v[84:87], v[154:157], v[194:197], v[84:87]
	ds_read_b128 v[214:217], v152 offset:3072
	v_mfma_f32_16x16x32_bf16 v[76:79], v[162:165], v[194:197], v[76:79]
	v_mfma_f32_16x16x32_bf16 v[124:127], v[158:161], v[174:177], v[124:127]
	v_mfma_f32_16x16x32_bf16 v[120:123], v[166:169], v[174:177], v[120:123]
	v_mfma_f32_16x16x32_bf16 v[116:119], v[158:161], v[182:185], v[116:119]
	v_mfma_f32_16x16x32_bf16 v[108:111], v[166:169], v[182:185], v[108:111]
	v_mfma_f32_16x16x32_bf16 v[100:103], v[158:161], v[190:193], v[100:103]
	v_mfma_f32_16x16x32_bf16 v[92:95], v[166:169], v[190:193], v[92:95]
	v_mfma_f32_16x16x32_bf16 v[84:87], v[158:161], v[198:201], v[84:87]
	v_mfma_f32_16x16x32_bf16 v[76:79], v[166:169], v[198:201], v[76:79]
	s_barrier
	s_setprio 0
	s_add_i32 s82, s66, s56
	s_mov_b32 m0, s82
	s_nop 0
	global_load_lds_dwordx4 v136, s[46:47]
	s_add_i32 m0, s82, 0x2000
	s_nop 0
	global_load_lds_dwordx4 v140, s[46:47]
	s_waitcnt lgkmcnt(0)
	s_setprio 1
	s_barrier
	v_mfma_f32_16x16x32_bf16 v[112:115], v[202:205], v[170:173], v[112:115]
	v_mfma_f32_16x16x32_bf16 v[104:107], v[210:213], v[170:173], v[104:107]
	v_mfma_f32_16x16x32_bf16 v[96:99], v[202:205], v[178:181], v[96:99]
	v_mfma_f32_16x16x32_bf16 v[88:91], v[210:213], v[178:181], v[88:91]
	v_mfma_f32_16x16x32_bf16 v[80:83], v[202:205], v[186:189], v[80:83]
	v_mfma_f32_16x16x32_bf16 v[72:75], v[210:213], v[186:189], v[72:75]
	v_mfma_f32_16x16x32_bf16 v[68:71], v[202:205], v[194:197], v[68:71]
	v_mfma_f32_16x16x32_bf16 v[64:67], v[210:213], v[194:197], v[64:67]
	v_mfma_f32_16x16x32_bf16 v[112:115], v[206:209], v[174:177], v[112:115]
	ds_read_b128 v[170:173], v151 offset:16384
	v_mfma_f32_16x16x32_bf16 v[104:107], v[214:217], v[174:177], v[104:107]
	v_mfma_f32_16x16x32_bf16 v[96:99], v[206:209], v[182:185], v[96:99]
	ds_read_b128 v[178:181], v151 offset:18432
	v_mfma_f32_16x16x32_bf16 v[88:91], v[214:217], v[182:185], v[88:91]
	v_mfma_f32_16x16x32_bf16 v[80:83], v[206:209], v[190:193], v[80:83]
	ds_read_b128 v[186:189], v151 offset:20480
	v_mfma_f32_16x16x32_bf16 v[72:75], v[214:217], v[190:193], v[72:75]
	v_mfma_f32_16x16x32_bf16 v[68:71], v[206:209], v[198:201], v[68:71]
	ds_read_b128 v[194:197], v151 offset:22528
	v_mfma_f32_16x16x32_bf16 v[64:67], v[214:217], v[198:201], v[64:67]
	s_barrier
	s_setprio 0
	s_mov_b32 m0, s57
	s_mov_b64 s[100:101], s[48:49]
	global_load_lds_dwordx4 v134, s[48:49]
	s_mov_b32 m0, s58
	s_nop 0
	global_load_lds_dwordx4 v138, s[48:49]
	ds_read_b128 v[174:177], v151 offset:17408
	ds_read_b128 v[182:185], v151 offset:19456
	ds_read_b128 v[190:193], v151 offset:21504
	ds_read_b128 v[198:201], v151 offset:23552
	s_waitcnt vmcnt(8)
	s_waitcnt lgkmcnt(0)
	s_setprio 1
	s_barrier
	v_mfma_f32_16x16x32_bf16 v[60:63], v[154:157], v[170:173], v[60:63]
	v_mfma_f32_16x16x32_bf16 v[56:59], v[162:165], v[170:173], v[56:59]
	v_mfma_f32_16x16x32_bf16 v[52:55], v[154:157], v[178:181], v[52:55]
	v_mfma_f32_16x16x32_bf16 v[44:47], v[162:165], v[178:181], v[44:47]
	v_mfma_f32_16x16x32_bf16 v[36:39], v[154:157], v[186:189], v[36:39]
	v_mfma_f32_16x16x32_bf16 v[28:31], v[162:165], v[186:189], v[28:31]
	v_mfma_f32_16x16x32_bf16 v[20:23], v[154:157], v[194:197], v[20:23]
	v_mfma_f32_16x16x32_bf16 v[12:15], v[162:165], v[194:197], v[12:15]
	v_mfma_f32_16x16x32_bf16 v[60:63], v[158:161], v[174:177], v[60:63]
	v_mfma_f32_16x16x32_bf16 v[56:59], v[166:169], v[174:177], v[56:59]
	v_mfma_f32_16x16x32_bf16 v[52:55], v[158:161], v[182:185], v[52:55]
	v_mfma_f32_16x16x32_bf16 v[44:47], v[166:169], v[182:185], v[44:47]
	v_mfma_f32_16x16x32_bf16 v[36:39], v[158:161], v[190:193], v[36:39]
	v_mfma_f32_16x16x32_bf16 v[28:31], v[166:169], v[190:193], v[28:31]
	v_mfma_f32_16x16x32_bf16 v[20:23], v[158:161], v[198:201], v[20:23]
	v_mfma_f32_16x16x32_bf16 v[12:15], v[166:169], v[198:201], v[12:15]
	s_barrier
	s_setprio 0
	s_add_u32 s82, s46, 0x100000
	s_addc_u32 s83, s47, 0
	s_add_i32 s84, s67, s56
	s_mov_b32 m0, s84
	s_nop 0
	global_load_lds_dwordx4 v136, s[82:83]
	s_add_i32 m0, s84, 0x2000
	s_nop 0
	global_load_lds_dwordx4 v140, s[82:83]
	v_add_u32_e32 v153, 0x18000, v148
	ds_read_b128 v[154:157], v153
	ds_read_b128 v[158:161], v153 offset:1024
	ds_read_b128 v[162:165], v153 offset:2048
	ds_read_b128 v[166:169], v153 offset:3072
	s_waitcnt vmcnt(6)
	s_setprio 1
	s_barrier
; #define PG8_STAGE(bufoff, gbase, voff) do { _Pragma("unroll") for (int _i = 0; _i < 2; ++_i) \
;         __builtin_amdgcn_global_load_lds((const unsigned*)((const char*)(gbase) + (voff)[_i]), (LAS unsigned*)(lds + (bufoff) + ldsw + _i * 8192), 16, 0, 0); } while (0)
; #define PG8_LDA(dst, b, h) do { _Pragma("unroll") for (int m = 0; m < 4; ++m) _Pragma("unroll") for (int k = 0; k < 2; ++k) dst[m][k] = *(const LAS bf16x8*)(lds + PG8_SA(b, h) + aoff + m * 2048 + k * 1024); } while (0)
; #define PG8_LDB(dst, b, h) do { _Pragma("unroll") for (int n = 0; n < 2; ++n) _Pragma("unroll") for (int k = 0; k < 2; ++k) dst[n][k] = *(const LAS bf16x8*)(lds + PG8_SB(b, h) + boff + n * 2048 + k * 1024); } while (0)
; #define PG8_MMA(ai, bj, At, Bt) do { __builtin_amdgcn_s_setprio(1); _Pragma("unroll") for (int m = 0; m < 4; ++m) _Pragma("unroll") for (int n = 0; n < 2; ++n) _Pragma("unroll") for (int k = 0; k < 2; ++k) \
;         acc[ai][bj][m][n] = __builtin_amdgcn_mfma_f32_16x16x32_bf16(Bt[n][k], At[m][k], acc[ai][bj][m][n], 0, 0, 0); __builtin_amdgcn_s_setprio(0); } while (0)
; #define PG8_WAIT_V(n) asm volatile("s_waitcnt vmcnt(" #n ")" ::: "memory")
; #define PG8_WAIT_L(n) asm volatile("s_waitcnt lgkmcnt(" #n ")" ::: "memory")
; #define PG8_BAR __builtin_amdgcn_s_barrier()
; #define PG8_SCHED __builtin_amdgcn_sched_barrier(0)
; template <class Epi, class Job>
; __device__ __forceinline__ void gemm_phase(LAS unsigned char* lds, const Job& S, const Epi& E) {
;     ...
;             PG8_WAIT_V(6); PG8_BAR; PG8_MMA(1, 1, At, B1); PG8_BAR;
;             PG8_LDB(B0, 1, 0); PG8_SCHED; PG8_LDA(At, 1, 0); PG8_STAGE(PG8_SA(0, 1), a2 + hstepA, voffA);
;             PG8_WAIT_L(8); PG8_BAR; PG8_WAIT_L(0); PG8_MMA(0, 0, At, B0); PG8_BAR; PG8_SCHED;
;             PG8_LDB(B1, 1, 1); PG8_STAGE(PG8_SB(1, 0), b3, voffB);
;             PG8_BAR; PG8_WAIT_L(0); PG8_MMA(0, 1, At, B1); PG8_BAR;
;             PG8_LDA(At, 1, 1); PG8_STAGE(PG8_SA(1, 0), a3, voffA);
;             PG8_BAR; PG8_WAIT_L(0); PG8_MMA(1, 0, At, B0); PG8_BAR; PG8_SCHED;
	v_mfma_f32_16x16x32_bf16 v[48:51], v[202:205], v[170:173], v[48:51]
	v_mfma_f32_16x16x32_bf16 v[40:43], v[210:213], v[170:173], v[40:43]
	v_mfma_f32_16x16x32_bf16 v[32:35], v[202:205], v[178:181], v[32:35]
	v_mfma_f32_16x16x32_bf16 v[24:27], v[210:213], v[178:181], v[24:27]
	v_mfma_f32_16x16x32_bf16 v[16:19], v[202:205], v[186:189], v[16:19]
	v_mfma_f32_16x16x32_bf16 v[8:11], v[210:213], v[186:189], v[8:11]
	v_mfma_f32_16x16x32_bf16 v[4:7], v[202:205], v[194:197], v[4:7]
	v_mfma_f32_16x16x32_bf16 v[0:3], v[210:213], v[194:197], v[0:3]
	v_mfma_f32_16x16x32_bf16 v[48:51], v[206:209], v[174:177], v[48:51]
	ds_read_b128 v[170:173], v151 offset:32768
	v_mfma_f32_16x16x32_bf16 v[40:43], v[214:217], v[174:177], v[40:43]
	v_mfma_f32_16x16x32_bf16 v[32:35], v[206:209], v[182:185], v[32:35]
	ds_read_b128 v[178:181], v151 offset:34816
	v_mfma_f32_16x16x32_bf16 v[24:27], v[214:217], v[182:185], v[24:27]
	v_mfma_f32_16x16x32_bf16 v[16:19], v[206:209], v[190:193], v[16:19]
	ds_read_b128 v[186:189], v151 offset:36864
	v_mfma_f32_16x16x32_bf16 v[8:11], v[214:217], v[190:193], v[8:11]
	v_mfma_f32_16x16x32_bf16 v[4:7], v[206:209], v[198:201], v[4:7]
	ds_read_b128 v[194:197], v151 offset:38912
	v_mfma_f32_16x16x32_bf16 v[0:3], v[214:217], v[198:201], v[0:3]
	s_barrier
	s_setprio 0
	s_add_i32 s82, 0, 0x18000
	v_add_u32_e32 v153, s82, v148
	s_add_u32 s48, s48, 0x100000
	s_addc_u32 s49, s49, 0
	s_mov_b32 m0, s59
	s_nop 0
	global_load_lds_dwordx4 v134, s[48:49]
	s_mov_b32 m0, s60
	s_nop 0
	global_load_lds_dwordx4 v138, s[48:49]
	ds_read_b128 v[174:177], v151 offset:33792
	ds_read_b128 v[182:185], v151 offset:35840
	ds_read_b128 v[190:193], v151 offset:37888
	ds_read_b128 v[198:201], v151 offset:39936
	s_waitcnt lgkmcnt(8)
	s_waitcnt lgkmcnt(0)
	s_setprio 1
	v_add_u32_e32 v153, 0x1c000, v148
	s_barrier
	v_mfma_f32_16x16x32_bf16 v[124:127], v[154:157], v[170:173], v[124:127]
	ds_read_b128 v[202:205], v153
	v_mfma_f32_16x16x32_bf16 v[120:123], v[162:165], v[170:173], v[120:123]
	v_mfma_f32_16x16x32_bf16 v[116:119], v[154:157], v[178:181], v[116:119]
	ds_read_b128 v[206:209], v153 offset:1024
	v_mfma_f32_16x16x32_bf16 v[108:111], v[162:165], v[178:181], v[108:111]
	v_mfma_f32_16x16x32_bf16 v[100:103], v[154:157], v[186:189], v[100:103]
	ds_read_b128 v[210:213], v153 offset:2048
	v_mfma_f32_16x16x32_bf16 v[92:95], v[162:165], v[186:189], v[92:95]
	v_mfma_f32_16x16x32_bf16 v[84:87], v[154:157], v[194:197], v[84:87]
	ds_read_b128 v[214:217], v153 offset:3072
	v_mfma_f32_16x16x32_bf16 v[76:79], v[162:165], v[194:197], v[76:79]
	v_mfma_f32_16x16x32_bf16 v[124:127], v[158:161], v[174:177], v[124:127]
	v_mfma_f32_16x16x32_bf16 v[120:123], v[166:169], v[174:177], v[120:123]
	v_mfma_f32_16x16x32_bf16 v[116:119], v[158:161], v[182:185], v[116:119]
	v_mfma_f32_16x16x32_bf16 v[108:111], v[166:169], v[182:185], v[108:111]
	v_mfma_f32_16x16x32_bf16 v[100:103], v[158:161], v[190:193], v[100:103]
	v_mfma_f32_16x16x32_bf16 v[92:95], v[166:169], v[190:193], v[92:95]
	v_mfma_f32_16x16x32_bf16 v[84:87], v[158:161], v[198:201], v[84:87]
	v_mfma_f32_16x16x32_bf16 v[76:79], v[166:169], v[198:201], v[76:79]
	s_barrier
	s_setprio 0
	s_add_i32 s48, 0, 0x1c000
	s_add_i32 s49, s82, s56
	v_add_u32_e32 v153, s48, v148
	s_add_u32 s98, s46, s8
	s_addc_u32 s99, s47, s9
	s_mov_b32 m0, s49
	s_nop 0
	global_load_lds_dwordx4 v136, s[98:99]
	s_add_i32 m0, s49, 0x2000
	s_nop 0
	global_load_lds_dwordx4 v140, s[98:99]
	s_waitcnt lgkmcnt(0)
	s_setprio 1
	s_barrier
	v_mfma_f32_16x16x32_bf16 v[112:115], v[202:205], v[170:173], v[112:115]
	v_mfma_f32_16x16x32_bf16 v[104:107], v[210:213], v[170:173], v[104:107]
	v_mfma_f32_16x16x32_bf16 v[96:99], v[202:205], v[178:181], v[96:99]
	v_mfma_f32_16x16x32_bf16 v[88:91], v[210:213], v[178:181], v[88:91]
	v_mfma_f32_16x16x32_bf16 v[80:83], v[202:205], v[186:189], v[80:83]
	v_mfma_f32_16x16x32_bf16 v[72:75], v[210:213], v[186:189], v[72:75]
	v_mfma_f32_16x16x32_bf16 v[68:71], v[202:205], v[194:197], v[68:71]
	v_mfma_f32_16x16x32_bf16 v[64:67], v[210:213], v[194:197], v[64:67]
	v_mfma_f32_16x16x32_bf16 v[112:115], v[206:209], v[174:177], v[112:115]
	ds_read_b128 v[170:173], v151 offset:49152
	v_mfma_f32_16x16x32_bf16 v[104:107], v[214:217], v[174:177], v[104:107]
	v_mfma_f32_16x16x32_bf16 v[96:99], v[206:209], v[182:185], v[96:99]
	ds_read_b128 v[178:181], v151 offset:51200
	v_mfma_f32_16x16x32_bf16 v[88:91], v[214:217], v[182:185], v[88:91]
	v_mfma_f32_16x16x32_bf16 v[80:83], v[206:209], v[190:193], v[80:83]
	ds_read_b128 v[186:189], v151 offset:53248
	v_mfma_f32_16x16x32_bf16 v[72:75], v[214:217], v[190:193], v[72:75]
	v_mfma_f32_16x16x32_bf16 v[68:71], v[206:209], v[198:201], v[68:71]
	ds_read_b128 v[194:197], v151 offset:55296
	v_mfma_f32_16x16x32_bf16 v[64:67], v[214:217], v[198:201], v[64:67]
	s_barrier
	s_setprio 0
	s_mov_b32 m0, s62
	s_add_u32 s100, s100, s8
	s_addc_u32 s101, s101, s9
	global_load_lds_dwordx4 v134, s[100:101]
	s_mov_b32 m0, s63
	s_nop 0
	global_load_lds_dwordx4 v138, s[100:101]
	ds_read_b128 v[174:177], v151 offset:50176
	ds_read_b128 v[182:185], v151 offset:52224
	ds_read_b128 v[190:193], v151 offset:54272
	ds_read_b128 v[198:201], v151 offset:56320
	s_waitcnt vmcnt(8)
	s_waitcnt lgkmcnt(0)
	s_setprio 1
	s_barrier
; #define PG8_STAGE(bufoff, gbase, voff) do { _Pragma("unroll") for (int _i = 0; _i < 2; ++_i) \
;         __builtin_amdgcn_global_load_lds((const unsigned*)((const char*)(gbase) + (voff)[_i]), (LAS unsigned*)(lds + (bufoff) + ldsw + _i * 8192), 16, 0, 0); } while (0)
; #define PG8_MMA(ai, bj, At, Bt) do { __builtin_amdgcn_s_setprio(1); _Pragma("unroll") for (int m = 0; m < 4; ++m) _Pragma("unroll") for (int n = 0; n < 2; ++n) _Pragma("unroll") for (int k = 0; k < 2; ++k) \
;         acc[ai][bj][m][n] = __builtin_amdgcn_mfma_f32_16x16x32_bf16(Bt[n][k], At[m][k], acc[ai][bj][m][n], 0, 0, 0); __builtin_amdgcn_s_setprio(0); } while (0)
; #define PG8_WAIT_V(n) asm volatile("s_waitcnt vmcnt(" #n ")" ::: "memory")
; #define PG8_WAIT_L(n) asm volatile("s_waitcnt lgkmcnt(" #n ")" ::: "memory")
; #define PG8_BAR __builtin_amdgcn_s_barrier()
; #define PG8_SCHED __builtin_amdgcn_sched_barrier(0)
; template <class Epi, class Job>
; __device__ __forceinline__ void gemm_phase(LAS unsigned char* lds, const Job& S, const Epi& E) {
;     ...
;             PG8_BAR; PG8_WAIT_L(0); PG8_MMA(1, 0, At, B0); PG8_BAR; PG8_SCHED;
;             PG8_STAGE(PG8_SB(1, 1), b3 + hstepB, voffB);
;             PG8_WAIT_V(6); PG8_BAR; PG8_MMA(1, 1, At, B1); PG8_BAR;
;         }
	v_mfma_f32_16x16x32_bf16 v[60:63], v[154:157], v[170:173], v[60:63]
	v_mfma_f32_16x16x32_bf16 v[56:59], v[162:165], v[170:173], v[56:59]
	v_mfma_f32_16x16x32_bf16 v[52:55], v[154:157], v[178:181], v[52:55]
	v_mfma_f32_16x16x32_bf16 v[44:47], v[162:165], v[178:181], v[44:47]
	v_mfma_f32_16x16x32_bf16 v[36:39], v[154:157], v[186:189], v[36:39]
	v_mfma_f32_16x16x32_bf16 v[28:31], v[162:165], v[186:189], v[28:31]
	v_mfma_f32_16x16x32_bf16 v[20:23], v[154:157], v[194:197], v[20:23]
	v_mfma_f32_16x16x32_bf16 v[12:15], v[162:165], v[194:197], v[12:15]
	v_mfma_f32_16x16x32_bf16 v[60:63], v[158:161], v[174:177], v[60:63]
	v_mfma_f32_16x16x32_bf16 v[56:59], v[166:169], v[174:177], v[56:59]
	v_mfma_f32_16x16x32_bf16 v[52:55], v[158:161], v[182:185], v[52:55]
	v_mfma_f32_16x16x32_bf16 v[44:47], v[166:169], v[182:185], v[44:47]
	v_mfma_f32_16x16x32_bf16 v[36:39], v[158:161], v[190:193], v[36:39]
	v_mfma_f32_16x16x32_bf16 v[28:31], v[166:169], v[190:193], v[28:31]
	v_mfma_f32_16x16x32_bf16 v[20:23], v[158:161], v[198:201], v[20:23]
	v_mfma_f32_16x16x32_bf16 v[12:15], v[166:169], v[198:201], v[12:15]
	s_barrier
	s_setprio 0
	s_add_u32 s46, s46, 0x100080
	s_addc_u32 s47, s47, 0
	s_add_i32 s48, s48, s56
	s_mov_b32 m0, s48
	s_nop 0
	global_load_lds_dwordx4 v136, s[46:47]
	s_add_i32 m0, s48, 0x2000
	s_nop 0
	global_load_lds_dwordx4 v140, s[46:47]
	ds_read_b128 v[154:157], v150
	ds_read_b128 v[158:161], v150 offset:1024
	ds_read_b128 v[162:165], v150 offset:2048
	ds_read_b128 v[166:169], v150 offset:3072
	s_waitcnt vmcnt(6)
	s_setprio 1
	s_barrier
	v_mfma_f32_16x16x32_bf16 v[48:51], v[202:205], v[170:173], v[48:51]
	v_mfma_f32_16x16x32_bf16 v[40:43], v[210:213], v[170:173], v[40:43]
	v_mfma_f32_16x16x32_bf16 v[32:35], v[202:205], v[178:181], v[32:35]
	v_mfma_f32_16x16x32_bf16 v[24:27], v[210:213], v[178:181], v[24:27]
	v_mfma_f32_16x16x32_bf16 v[16:19], v[202:205], v[186:189], v[16:19]
	v_mfma_f32_16x16x32_bf16 v[8:11], v[210:213], v[186:189], v[8:11]
	v_mfma_f32_16x16x32_bf16 v[4:7], v[202:205], v[194:197], v[4:7]
	v_mfma_f32_16x16x32_bf16 v[0:3], v[210:213], v[194:197], v[0:3]
	v_mfma_f32_16x16x32_bf16 v[48:51], v[206:209], v[174:177], v[48:51]
	ds_read_b128 v[170:173], v151
	v_mfma_f32_16x16x32_bf16 v[40:43], v[214:217], v[174:177], v[40:43]
	v_mfma_f32_16x16x32_bf16 v[32:35], v[206:209], v[182:185], v[32:35]
	ds_read_b128 v[178:181], v151 offset:2048
	v_mfma_f32_16x16x32_bf16 v[24:27], v[214:217], v[182:185], v[24:27]
	v_mfma_f32_16x16x32_bf16 v[16:19], v[206:209], v[190:193], v[16:19]
	ds_read_b128 v[186:189], v151 offset:4096
	v_mfma_f32_16x16x32_bf16 v[8:11], v[214:217], v[190:193], v[8:11]
	v_mfma_f32_16x16x32_bf16 v[4:7], v[206:209], v[198:201], v[4:7]
	ds_read_b128 v[194:197], v151 offset:6144
	v_mfma_f32_16x16x32_bf16 v[0:3], v[214:217], v[198:201], v[0:3]
	s_barrier
	s_setprio 0
	s_add_i32 s81, s81, 2
	s_add_u32 s36, s36, 0x100
	s_addc_u32 s37, s37, 0
	s_add_u32 s79, s79, 0x100
	s_addc_u32 s80, s80, 0
	s_cmp_gt_u32 s81, 61
	s_cbranch_scc0 .LBB0_457
; __device__ __forceinline__ unsigned cvt_pk_bf16(float lo, float hi) { unsigned r; asm volatile("v_cvt_pk_bf16_f32 %0, %1, %2" : "=v"(r) : "v"(lo), "v"(hi)); return r; }
;     __device__ __forceinline__ void operator()(const f32x4 (&acc)[2][2][4][2], const Unit& u, int wr, int wc, int fr, int fq) const {
;         const int row0 = u.orow + wr * 64 + fr, col0 = u.ocol + wc * 32 + 8 * fq;
; #pragma unroll
;         for (int ai = 0; ai < 2; ++ai)
; #pragma unroll
;             for (int m = 0; m < 4; ++m) { bf16_t* rowp = O + (size_t)(row0 + ai * HALF + m * 16) * ldc + col0;
; #pragma unroll
;                 for (int bj = 0; bj < 2; ++bj) { const f32x4 v0 = acc[ai][bj][m][0], v1 = acc[ai][bj][m][1];
;                     u32x4 w; w.x = cvt_pk_bf16(v0[0], v0[1]); w.y = cvt_pk_bf16(v0[2], v0[3]); w.z = cvt_pk_bf16(v1[0], v1[1]); w.w = cvt_pk_bf16(v1[2], v1[3]);
;                     if (nt) __builtin_nontemporal_store(w, (u32x4*)(rowp + bj * HALF)); else *(u32x4*)(rowp + bj * HALF) = w; } }
;     }
; template <class Epi, class Job>
; __device__ __forceinline__ void gemm_phase(LAS unsigned char* lds, const Job& S, const Epi& E) {
;     ...
;         E(acc, cur, wr, wc, fr, fq);
;         if (!has_next) break;
	s_waitcnt lgkmcnt(0)
	v_add_u32_e32 v146, s78, v131
	v_ashrrev_i32_e32 v147, 31, v146
	v_add_u32_e32 v154, s77, v149
	v_lshlrev_b64 v[146:147], 13, v[146:147]
	v_ashrrev_i32_e32 v155, 31, v154
	v_lshl_add_u64 v[146:147], s[18:19], 0, v[146:147]
	v_lshl_add_u64 v[146:147], v[154:155], 1, v[146:147]
	v_cvt_pk_bf16_f32 v124, v124, v125
	v_cvt_pk_bf16_f32 v125, v126, v127
	v_cvt_pk_bf16_f32 v126, v120, v121
	v_cvt_pk_bf16_f32 v127, v122, v123
	global_store_dwordx4 v[146:147], v[124:127], off
	v_cvt_pk_bf16_f32 v112, v112, v113
	v_cvt_pk_bf16_f32 v113, v114, v115
	v_cvt_pk_bf16_f32 v114, v104, v105
	v_cvt_pk_bf16_f32 v115, v106, v107
	global_store_dwordx4 v[146:147], v[112:115], off offset:256
	v_cvt_pk_bf16_f32 v104, v116, v117
	v_cvt_pk_bf16_f32 v105, v118, v119
	v_cvt_pk_bf16_f32 v106, v108, v109
	v_add_co_u32_e32 v108, vcc, s68, v146
	s_nop 0
	v_lshl_add_u64 v[112:113], v[146:147], 0, s[10:11]
	v_addc_co_u32_e32 v109, vcc, 0, v147, vcc
	v_cvt_pk_bf16_f32 v107, v110, v111
	global_store_dwordx4 v[108:109], v[104:107], off
	v_cvt_pk_bf16_f32 v96, v96, v97
	v_cvt_pk_bf16_f32 v97, v98, v99
	v_cvt_pk_bf16_f32 v98, v88, v89
	v_cvt_pk_bf16_f32 v99, v90, v91
	global_store_dwordx4 v[112:113], v[96:99], off offset:256
	v_cvt_pk_bf16_f32 v88, v100, v101
	v_cvt_pk_bf16_f32 v89, v102, v103
	v_cvt_pk_bf16_f32 v90, v92, v93
	v_add_co_u32_e32 v92, vcc, s69, v146
	s_nop 0
	v_lshl_add_u64 v[96:97], v[146:147], 0, s[12:13]
	v_addc_co_u32_e32 v93, vcc, 0, v147, vcc
	v_cvt_pk_bf16_f32 v91, v94, v95
	global_store_dwordx4 v[92:93], v[88:91], off
	v_cvt_pk_bf16_f32 v80, v80, v81
	v_cvt_pk_bf16_f32 v81, v82, v83
	v_cvt_pk_bf16_f32 v82, v72, v73
	v_cvt_pk_bf16_f32 v83, v74, v75
	global_store_dwordx4 v[96:97], v[80:83], off offset:256
	v_cvt_pk_bf16_f32 v72, v84, v85
	v_cvt_pk_bf16_f32 v73, v86, v87
	v_cvt_pk_bf16_f32 v74, v76, v77
	v_add_co_u32_e32 v76, vcc, s70, v146
	s_nop 0
	v_lshl_add_u64 v[80:81], v[146:147], 0, s[20:21]
	v_addc_co_u32_e32 v77, vcc, 0, v147, vcc
	v_cvt_pk_bf16_f32 v75, v78, v79
	global_store_dwordx4 v[76:77], v[72:75], off
	v_cvt_pk_bf16_f32 v68, v68, v69
	v_cvt_pk_bf16_f32 v69, v70, v71
	v_cvt_pk_bf16_f32 v70, v64, v65
	v_cvt_pk_bf16_f32 v71, v66, v67
	global_store_dwordx4 v[80:81], v[68:71], off offset:256
	v_cvt_pk_bf16_f32 v60, v60, v61
	v_cvt_pk_bf16_f32 v61, v62, v63
	v_cvt_pk_bf16_f32 v62, v56, v57
	v_add_co_u32_e32 v56, vcc, s71, v146
	v_lshl_add_u64 v[64:65], v[146:147], 0, s[6:7]
	s_nop 0
	v_addc_co_u32_e32 v57, vcc, 0, v147, vcc
	v_cvt_pk_bf16_f32 v63, v58, v59
	global_store_dwordx4 v[56:57], v[60:63], off
	v_cvt_pk_bf16_f32 v48, v48, v49
	v_cvt_pk_bf16_f32 v49, v50, v51
	v_cvt_pk_bf16_f32 v50, v40, v41
	v_cvt_pk_bf16_f32 v51, v42, v43
	global_store_dwordx4 v[64:65], v[48:51], off offset:256
	v_cvt_pk_bf16_f32 v40, v52, v53
	v_cvt_pk_bf16_f32 v41, v54, v55
	v_cvt_pk_bf16_f32 v42, v44, v45
	v_add_co_u32_e32 v44, vcc, s72, v146
	s_nop 0
	v_lshl_add_u64 v[48:49], v[146:147], 0, s[22:23]
	v_addc_co_u32_e32 v45, vcc, 0, v147, vcc
	v_cvt_pk_bf16_f32 v43, v46, v47
	global_store_dwordx4 v[44:45], v[40:43], off
	v_cvt_pk_bf16_f32 v32, v32, v33
	v_cvt_pk_bf16_f32 v33, v34, v35
	v_cvt_pk_bf16_f32 v34, v24, v25
	v_cvt_pk_bf16_f32 v35, v26, v27
	global_store_dwordx4 v[48:49], v[32:35], off offset:256
	v_cvt_pk_bf16_f32 v24, v36, v37
	v_cvt_pk_bf16_f32 v25, v38, v39
	v_cvt_pk_bf16_f32 v26, v28, v29
	v_add_co_u32_e32 v28, vcc, s73, v146
	s_nop 0
	v_lshl_add_u64 v[32:33], v[146:147], 0, s[24:25]
	v_addc_co_u32_e32 v29, vcc, 0, v147, vcc
	v_cvt_pk_bf16_f32 v27, v30, v31
	global_store_dwordx4 v[28:29], v[24:27], off
	v_cvt_pk_bf16_f32 v16, v16, v17
	v_cvt_pk_bf16_f32 v17, v18, v19
	v_cvt_pk_bf16_f32 v18, v8, v9
	v_cvt_pk_bf16_f32 v19, v10, v11
	global_store_dwordx4 v[32:33], v[16:19], off offset:256
	v_cvt_pk_bf16_f32 v8, v20, v21
	v_cvt_pk_bf16_f32 v9, v22, v23
	v_cvt_pk_bf16_f32 v10, v12, v13
	v_add_co_u32_e32 v12, vcc, s74, v146
	s_nop 0
	v_lshl_add_u64 v[16:17], v[146:147], 0, s[26:27]
	v_addc_co_u32_e32 v13, vcc, 0, v147, vcc
	s_and_b64 vcc, exec, s[4:5]
	s_mov_b32 s77, s76
	s_mov_b32 s78, s75
	s_mov_b64 s[46:47], s[30:31]
	s_mov_b64 s[36:37], s[28:29]
	v_cvt_pk_bf16_f32 v11, v14, v15
	global_store_dwordx4 v[12:13], v[8:11], off
	v_cvt_pk_bf16_f32 v4, v4, v5
	v_cvt_pk_bf16_f32 v5, v6, v7
	v_cvt_pk_bf16_f32 v6, v0, v1
	v_cvt_pk_bf16_f32 v7, v2, v3
	global_store_dwordx4 v[16:17], v[4:7], off offset:256
	s_cbranch_vccz .LBB0_450
	s_waitcnt vmcnt(0)
	s_cmpk_gt_u32 s50, 0xff
	s_cbranch_scc1 .LBB0_461
	s_barrier
